# P5 mid-K hook: lagging wave group issues its gate loads one barrier earlier (after its last MFMA) so both groups' hook loads are in flight together
# baseline (speedup 1.0000x reference)
.LBB0_546:
	s_add_u32 s12, s52, s10
	s_addc_u32 s13, s53, s11
	s_add_u32 s12, s12, 0x100
	s_addc_u32 s13, s13, 0
	s_add_u32 s30, s45, s10
	s_addc_u32 s31, s47, s11
	s_cmpk_eq_i32 s10, 0x700
	s_cselect_b32 s55, s14, s13
	s_cselect_b32 s54, s15, s12
	s_cselect_b32 s13, s26, s31
	s_cselect_b32 s12, s27, s30
	s_add_i32 s30, 0, 0x10000
	v_add_u32_e32 v0, s30, v160
	s_add_i32 s34, 0, 0x14000
	ds_read_b128 v[132:135], v0
	ds_read_b128 v[164:167], v0 offset:1024
	ds_read_b128 v[168:171], v0 offset:2048
	ds_read_b128 v[172:175], v0 offset:3072
	v_add_u32_e32 v0, s34, v160
	ds_read_b128 v[198:201], v0
	ds_read_b128 v[202:205], v0 offset:1024
	ds_read_b128 v[206:209], v0 offset:2048
	ds_read_b128 v[210:213], v0 offset:3072
	v_lshl_add_u64 v[2:3], v[154:155], 0, s[10:11]
	s_add_i32 m0, s58, 0xc000
	ds_read_b128 v[216:219], v163
	ds_read_b128 v[220:223], v163 offset:1024
	ds_read_b128 v[224:227], v163 offset:2048
	ds_read_b128 v[228:231], v163 offset:3072
	ds_read_b128 v[232:235], v163 offset:4096
	ds_read_b128 v[236:239], v163 offset:5120
	ds_read_b128 v[240:243], v163 offset:6144
	ds_read_b128 v[244:247], v163 offset:7168
	global_load_lds_dwordx4 v[2:3], off
	v_lshl_add_u64 v[2:3], v[156:157], 0, s[10:11]
	s_add_i32 m0, s58, 0xe000
	s_nop 0
	global_load_lds_dwordx4 v[2:3], off
	s_waitcnt vmcnt(8)
	s_waitcnt lgkmcnt(0)
	s_barrier
	s_setprio 1
	s_waitcnt lgkmcnt(0)
	v_mfma_f32_16x16x32_bf16 v[128:131], v[132:135], v[216:219], v[128:131]
	v_mfma_f32_16x16x32_bf16 v[124:127], v[168:171], v[216:219], v[124:127]
	v_mfma_f32_16x16x32_bf16 v[112:115], v[132:135], v[224:227], v[112:115]
	v_mfma_f32_16x16x32_bf16 v[108:111], v[168:171], v[224:227], v[108:111]
	v_mfma_f32_16x16x32_bf16 v[96:99], v[132:135], v[232:235], v[96:99]
	v_mfma_f32_16x16x32_bf16 v[92:95], v[168:171], v[232:235], v[92:95]
	v_mfma_f32_16x16x32_bf16 v[80:83], v[132:135], v[240:243], v[80:83]
	v_mfma_f32_16x16x32_bf16 v[76:79], v[168:171], v[240:243], v[76:79]
	v_mfma_f32_16x16x32_bf16 v[128:131], v[164:167], v[220:223], v[128:131]
	v_mfma_f32_16x16x32_bf16 v[124:127], v[172:175], v[220:223], v[124:127]
	v_mfma_f32_16x16x32_bf16 v[112:115], v[164:167], v[228:231], v[112:115]
	v_mfma_f32_16x16x32_bf16 v[108:111], v[172:175], v[228:231], v[108:111]
	v_mfma_f32_16x16x32_bf16 v[96:99], v[164:167], v[236:239], v[96:99]
	v_mfma_f32_16x16x32_bf16 v[92:95], v[172:175], v[236:239], v[92:95]
	v_mfma_f32_16x16x32_bf16 v[80:83], v[164:167], v[244:247], v[80:83]
	v_mfma_f32_16x16x32_bf16 v[76:79], v[172:175], v[244:247], v[76:79]
	s_setprio 0
	s_setprio 1
	v_mfma_f32_16x16x32_bf16 v[120:123], v[198:201], v[216:219], v[120:123]
	v_mfma_f32_16x16x32_bf16 v[116:119], v[206:209], v[216:219], v[116:119]
	v_mfma_f32_16x16x32_bf16 v[104:107], v[198:201], v[224:227], v[104:107]
	v_mfma_f32_16x16x32_bf16 v[100:103], v[206:209], v[224:227], v[100:103]
	v_mfma_f32_16x16x32_bf16 v[88:91], v[198:201], v[232:235], v[88:91]
	v_mfma_f32_16x16x32_bf16 v[84:87], v[206:209], v[232:235], v[84:87]
	v_mfma_f32_16x16x32_bf16 v[72:75], v[198:201], v[240:243], v[72:75]
	v_mfma_f32_16x16x32_bf16 v[68:71], v[206:209], v[240:243], v[68:71]
	v_mfma_f32_16x16x32_bf16 v[120:123], v[202:205], v[220:223], v[120:123]
	v_mfma_f32_16x16x32_bf16 v[116:119], v[210:213], v[220:223], v[116:119]
	v_mfma_f32_16x16x32_bf16 v[104:107], v[202:205], v[228:231], v[104:107]
	v_mfma_f32_16x16x32_bf16 v[100:103], v[210:213], v[228:231], v[100:103]
	v_mfma_f32_16x16x32_bf16 v[88:91], v[202:205], v[236:239], v[88:91]
	v_mfma_f32_16x16x32_bf16 v[84:87], v[210:213], v[236:239], v[84:87]
	v_mfma_f32_16x16x32_bf16 v[72:75], v[202:205], v[244:247], v[72:75]
	v_mfma_f32_16x16x32_bf16 v[68:71], v[210:213], v[244:247], v[68:71]
	s_setprio 0
	s_barrier
	s_add_i32 s30, s30, s57
	v_lshl_add_u64 v[176:177], s[12:13], 0, v[138:139]
	s_mov_b32 m0, s30
	ds_read_b128 v[216:219], v163 offset:16384
	ds_read_b128 v[220:223], v163 offset:17408
	ds_read_b128 v[224:227], v163 offset:18432
	ds_read_b128 v[228:231], v163 offset:19456
	ds_read_b128 v[232:235], v163 offset:20480
	ds_read_b128 v[236:239], v163 offset:21504
	ds_read_b128 v[240:243], v163 offset:22528
	ds_read_b128 v[244:247], v163 offset:23552
	global_load_lds_dwordx4 v[176:177], off
	s_add_i32 m0, s30, 0x2000
	s_add_u32 s30, s12, 0x40000
	v_lshl_add_u64 v[248:249], s[12:13], 0, v[142:143]
	s_addc_u32 s31, s13, 0
	s_add_i32 s34, s34, s57
	global_load_lds_dwordx4 v[248:249], off
	v_lshl_add_u64 v[2:3], s[30:31], 0, v[138:139]
	s_mov_b32 m0, s34
	v_lshl_add_u64 v[250:251], s[54:55], 0, v[136:137]
	global_load_lds_dwordx4 v[2:3], off
	v_lshl_add_u64 v[2:3], s[30:31], 0, v[142:143]
	s_add_i32 m0, s34, 0x2000
	v_lshl_add_u64 v[252:253], s[54:55], 0, v[140:141]
	global_load_lds_dwordx4 v[2:3], off
	s_mov_b32 m0, s58
	s_nop 0
	global_load_lds_dwordx4 v[250:251], off
	s_mov_b32 m0, s59
	s_nop 0
	global_load_lds_dwordx4 v[252:253], off
	s_waitcnt vmcnt(8)
	s_waitcnt lgkmcnt(0)
	s_barrier
	s_setprio 1
	s_waitcnt lgkmcnt(0)
	v_mfma_f32_16x16x32_bf16 v[64:67], v[132:135], v[216:219], v[64:67]
	v_mfma_f32_16x16x32_bf16 v[60:63], v[168:171], v[216:219], v[60:63]
	v_mfma_f32_16x16x32_bf16 v[48:51], v[132:135], v[224:227], v[48:51]
	v_mfma_f32_16x16x32_bf16 v[44:47], v[168:171], v[224:227], v[44:47]
	v_mfma_f32_16x16x32_bf16 v[32:35], v[132:135], v[232:235], v[32:35]
	v_mfma_f32_16x16x32_bf16 v[28:31], v[168:171], v[232:235], v[28:31]
	v_mfma_f32_16x16x32_bf16 v[16:19], v[132:135], v[240:243], v[16:19]
	v_mfma_f32_16x16x32_bf16 v[12:15], v[168:171], v[240:243], v[12:15]
	v_mfma_f32_16x16x32_bf16 v[64:67], v[164:167], v[220:223], v[64:67]
	v_mfma_f32_16x16x32_bf16 v[60:63], v[172:175], v[220:223], v[60:63]
	v_mfma_f32_16x16x32_bf16 v[48:51], v[164:167], v[228:231], v[48:51]
	v_mfma_f32_16x16x32_bf16 v[44:47], v[172:175], v[228:231], v[44:47]
	v_mfma_f32_16x16x32_bf16 v[32:35], v[164:167], v[236:239], v[32:35]
	v_mfma_f32_16x16x32_bf16 v[28:31], v[172:175], v[236:239], v[28:31]
	v_mfma_f32_16x16x32_bf16 v[16:19], v[164:167], v[244:247], v[16:19]
	v_mfma_f32_16x16x32_bf16 v[12:15], v[172:175], v[244:247], v[12:15]
	s_setprio 0
	s_setprio 1
	v_mfma_f32_16x16x32_bf16 v[56:59], v[198:201], v[216:219], v[56:59]
	v_mfma_f32_16x16x32_bf16 v[52:55], v[206:209], v[216:219], v[52:55]
	v_mfma_f32_16x16x32_bf16 v[40:43], v[198:201], v[224:227], v[40:43]
	v_mfma_f32_16x16x32_bf16 v[36:39], v[206:209], v[224:227], v[36:39]
	v_mfma_f32_16x16x32_bf16 v[24:27], v[198:201], v[232:235], v[24:27]
	v_mfma_f32_16x16x32_bf16 v[20:23], v[206:209], v[232:235], v[20:23]
	v_mfma_f32_16x16x32_bf16 v[8:11], v[198:201], v[240:243], v[8:11]
	v_mfma_f32_16x16x32_bf16 v[2:5], v[206:209], v[240:243], v[4:7]
	v_mfma_f32_16x16x32_bf16 v[56:59], v[202:205], v[220:223], v[56:59]
	v_mfma_f32_16x16x32_bf16 v[52:55], v[210:213], v[220:223], v[52:55]
	v_mfma_f32_16x16x32_bf16 v[40:43], v[202:205], v[228:231], v[40:43]
	v_mfma_f32_16x16x32_bf16 v[36:39], v[210:213], v[228:231], v[36:39]
	v_mfma_f32_16x16x32_bf16 v[24:27], v[202:205], v[236:239], v[24:27]
	v_mfma_f32_16x16x32_bf16 v[20:23], v[210:213], v[236:239], v[20:23]
	v_mfma_f32_16x16x32_bf16 v[8:11], v[202:205], v[244:247], v[8:11]
	v_mfma_f32_16x16x32_bf16 v[2:5], v[210:213], v[244:247], v[2:5]
	s_setprio 0
	s_barrier
	s_add_i32 s34, 0, 0x18000
	v_add_u32_e32 v0, s34, v160
	s_add_i32 s35, 0, 0x1c000
	ds_read_b128 v[132:135], v0
	ds_read_b128 v[164:167], v0 offset:1024
	ds_read_b128 v[168:171], v0 offset:2048
	ds_read_b128 v[172:175], v0 offset:3072
	v_add_u32_e32 v0, s35, v160
	ds_read_b128 v[198:201], v0
	ds_read_b128 v[202:205], v0 offset:1024
	ds_read_b128 v[206:209], v0 offset:2048
	ds_read_b128 v[210:213], v0 offset:3072
	s_add_u32 s30, s54, 0x40000
	s_addc_u32 s31, s55, 0
	s_mov_b32 m0, s60
	v_lshl_add_u64 v[6:7], s[30:31], 0, v[136:137]
	ds_read_b128 v[216:219], v163 offset:32768
	ds_read_b128 v[220:223], v163 offset:33792
	ds_read_b128 v[224:227], v163 offset:34816
	ds_read_b128 v[228:231], v163 offset:35840
	ds_read_b128 v[232:235], v163 offset:36864
	ds_read_b128 v[236:239], v163 offset:37888
	ds_read_b128 v[240:243], v163 offset:38912
	ds_read_b128 v[244:247], v163 offset:39936
	global_load_lds_dwordx4 v[6:7], off
	v_lshl_add_u64 v[6:7], s[30:31], 0, v[140:141]
	s_mov_b32 m0, s61
	s_nop 0
	global_load_lds_dwordx4 v[6:7], off
	s_waitcnt vmcnt(8)
	s_waitcnt lgkmcnt(0)
	s_barrier
	s_setprio 1
	s_waitcnt lgkmcnt(0)
	v_mfma_f32_16x16x32_bf16 v[128:131], v[132:135], v[216:219], v[128:131]
	v_mfma_f32_16x16x32_bf16 v[124:127], v[168:171], v[216:219], v[124:127]
	v_mfma_f32_16x16x32_bf16 v[112:115], v[132:135], v[224:227], v[112:115]
	v_mfma_f32_16x16x32_bf16 v[108:111], v[168:171], v[224:227], v[108:111]
	v_mfma_f32_16x16x32_bf16 v[96:99], v[132:135], v[232:235], v[96:99]
	v_mfma_f32_16x16x32_bf16 v[92:95], v[168:171], v[232:235], v[92:95]
	v_mfma_f32_16x16x32_bf16 v[80:83], v[132:135], v[240:243], v[80:83]
	v_mfma_f32_16x16x32_bf16 v[76:79], v[168:171], v[240:243], v[76:79]
	v_mfma_f32_16x16x32_bf16 v[128:131], v[164:167], v[220:223], v[128:131]
	v_mfma_f32_16x16x32_bf16 v[124:127], v[172:175], v[220:223], v[124:127]
	v_mfma_f32_16x16x32_bf16 v[112:115], v[164:167], v[228:231], v[112:115]
	v_mfma_f32_16x16x32_bf16 v[108:111], v[172:175], v[228:231], v[108:111]
	v_mfma_f32_16x16x32_bf16 v[96:99], v[164:167], v[236:239], v[96:99]
	v_mfma_f32_16x16x32_bf16 v[92:95], v[172:175], v[236:239], v[92:95]
	v_mfma_f32_16x16x32_bf16 v[80:83], v[164:167], v[244:247], v[80:83]
	v_mfma_f32_16x16x32_bf16 v[76:79], v[172:175], v[244:247], v[76:79]
	s_setprio 0
	s_setprio 1
	v_mfma_f32_16x16x32_bf16 v[120:123], v[198:201], v[216:219], v[120:123]
	v_mfma_f32_16x16x32_bf16 v[116:119], v[206:209], v[216:219], v[116:119]
	v_mfma_f32_16x16x32_bf16 v[104:107], v[198:201], v[224:227], v[104:107]
	v_mfma_f32_16x16x32_bf16 v[100:103], v[206:209], v[224:227], v[100:103]
	v_mfma_f32_16x16x32_bf16 v[88:91], v[198:201], v[232:235], v[88:91]
	v_mfma_f32_16x16x32_bf16 v[84:87], v[206:209], v[232:235], v[84:87]
	v_mfma_f32_16x16x32_bf16 v[72:75], v[198:201], v[240:243], v[72:75]
	v_mfma_f32_16x16x32_bf16 v[68:71], v[206:209], v[240:243], v[68:71]
	v_mfma_f32_16x16x32_bf16 v[120:123], v[202:205], v[220:223], v[120:123]
	v_mfma_f32_16x16x32_bf16 v[116:119], v[210:213], v[220:223], v[116:119]
	v_mfma_f32_16x16x32_bf16 v[104:107], v[202:205], v[228:231], v[104:107]
	v_mfma_f32_16x16x32_bf16 v[100:103], v[210:213], v[228:231], v[100:103]
	v_mfma_f32_16x16x32_bf16 v[88:91], v[202:205], v[236:239], v[88:91]
	v_mfma_f32_16x16x32_bf16 v[84:87], v[210:213], v[236:239], v[84:87]
	v_mfma_f32_16x16x32_bf16 v[72:75], v[202:205], v[244:247], v[72:75]
	v_mfma_f32_16x16x32_bf16 v[68:71], v[210:213], v[244:247], v[68:71]
	s_setprio 0
	s_barrier
	s_add_i32 s30, s34, s57
	v_lshl_add_u64 v[6:7], v[176:177], 0, s[90:91]
	s_mov_b32 m0, s30
	ds_read_b128 v[216:219], v163 offset:49152
	ds_read_b128 v[220:223], v163 offset:50176
	ds_read_b128 v[224:227], v163 offset:51200
	ds_read_b128 v[228:231], v163 offset:52224
	ds_read_b128 v[232:235], v163 offset:53248
	ds_read_b128 v[236:239], v163 offset:54272
	ds_read_b128 v[240:243], v163 offset:55296
	ds_read_b128 v[244:247], v163 offset:56320
	global_load_lds_dwordx4 v[6:7], off
	s_add_i32 m0, s30, 0x2000
	s_add_u32 s12, s12, 0x40080
	v_lshl_add_u64 v[6:7], v[248:249], 0, s[90:91]
	s_addc_u32 s13, s13, 0
	s_add_i32 s30, s35, s57
	global_load_lds_dwordx4 v[6:7], off
	v_lshl_add_u64 v[6:7], s[12:13], 0, v[138:139]
	s_mov_b32 m0, s30
	s_nop 0
	global_load_lds_dwordx4 v[6:7], off
	v_lshl_add_u64 v[6:7], s[12:13], 0, v[142:143]
	s_add_i32 m0, s30, 0x2000
	s_nop 0
	global_load_lds_dwordx4 v[6:7], off
	v_lshl_add_u64 v[6:7], v[250:251], 0, s[90:91]
	s_mov_b32 m0, s64
	s_nop 0
	global_load_lds_dwordx4 v[6:7], off
	v_lshl_add_u64 v[6:7], v[252:253], 0, s[90:91]
	s_mov_b32 m0, s65
	s_nop 0
	global_load_lds_dwordx4 v[6:7], off
	s_waitcnt vmcnt(8)
	s_waitcnt lgkmcnt(0)
	s_barrier
	s_setprio 1
	s_waitcnt lgkmcnt(0)
	v_mfma_f32_16x16x32_bf16 v[64:67], v[132:135], v[216:219], v[64:67]
	v_mfma_f32_16x16x32_bf16 v[60:63], v[168:171], v[216:219], v[60:63]
	v_mfma_f32_16x16x32_bf16 v[48:51], v[132:135], v[224:227], v[48:51]
	v_mfma_f32_16x16x32_bf16 v[44:47], v[168:171], v[224:227], v[44:47]
	v_mfma_f32_16x16x32_bf16 v[32:35], v[132:135], v[232:235], v[32:35]
	v_mfma_f32_16x16x32_bf16 v[28:31], v[168:171], v[232:235], v[28:31]
	v_mfma_f32_16x16x32_bf16 v[16:19], v[132:135], v[240:243], v[16:19]
	v_mfma_f32_16x16x32_bf16 v[12:15], v[168:171], v[240:243], v[12:15]
	v_mfma_f32_16x16x32_bf16 v[64:67], v[164:167], v[220:223], v[64:67]
	v_mfma_f32_16x16x32_bf16 v[60:63], v[172:175], v[220:223], v[60:63]
	v_mfma_f32_16x16x32_bf16 v[48:51], v[164:167], v[228:231], v[48:51]
	v_mfma_f32_16x16x32_bf16 v[44:47], v[172:175], v[228:231], v[44:47]
	v_mfma_f32_16x16x32_bf16 v[32:35], v[164:167], v[236:239], v[32:35]
	v_mfma_f32_16x16x32_bf16 v[28:31], v[172:175], v[236:239], v[28:31]
	v_mfma_f32_16x16x32_bf16 v[16:19], v[164:167], v[244:247], v[16:19]
	v_mfma_f32_16x16x32_bf16 v[12:15], v[172:175], v[244:247], v[12:15]
	s_setprio 0
	s_setprio 1
	v_mfma_f32_16x16x32_bf16 v[56:59], v[198:201], v[216:219], v[56:59]
	v_mfma_f32_16x16x32_bf16 v[52:55], v[206:209], v[216:219], v[52:55]
	v_mfma_f32_16x16x32_bf16 v[40:43], v[198:201], v[224:227], v[40:43]
	v_mfma_f32_16x16x32_bf16 v[36:39], v[206:209], v[224:227], v[36:39]
	v_mfma_f32_16x16x32_bf16 v[24:27], v[198:201], v[232:235], v[24:27]
	v_mfma_f32_16x16x32_bf16 v[20:23], v[206:209], v[232:235], v[20:23]
	v_mfma_f32_16x16x32_bf16 v[6:9], v[198:201], v[240:243], v[8:11]
	v_mfma_f32_16x16x32_bf16 v[2:5], v[206:209], v[240:243], v[2:5]
	v_mfma_f32_16x16x32_bf16 v[56:59], v[202:205], v[220:223], v[56:59]
	v_mfma_f32_16x16x32_bf16 v[52:55], v[210:213], v[220:223], v[52:55]
	v_mfma_f32_16x16x32_bf16 v[40:43], v[202:205], v[228:231], v[40:43]
	v_mfma_f32_16x16x32_bf16 v[36:39], v[210:213], v[228:231], v[36:39]
	v_mfma_f32_16x16x32_bf16 v[24:27], v[202:205], v[236:239], v[24:27]
	v_mfma_f32_16x16x32_bf16 v[20:23], v[210:213], v[236:239], v[20:23]
	v_mfma_f32_16x16x32_bf16 v[8:11], v[202:205], v[244:247], v[6:9]
	v_mfma_f32_16x16x32_bf16 v[4:7], v[210:213], v[244:247], v[2:5]
	s_setprio 0
	s_cmpk_lg_i32 s10, 0x300
	s_cbranch_scc1 .Lp5_noearly
	s_and_b64 vcc, exec, s[8:9]
	s_cbranch_vccnz .Lp5_noearly
	v_add_u32_e32 v132, s29, v147
	v_lshl_add_u32 v2, v158, 3, s28
	v_ashrrev_i32_e32 v133, 31, v132
	v_ashrrev_i32_e32 v3, 31, v2
	v_lshlrev_b64 v[132:133], 12, v[132:133]
	v_lshlrev_b64 v[2:3], 1, v[2:3]
	v_lshl_add_u64 v[2:3], s[92:93], 0, v[2:3]
	v_lshl_add_u64 v[2:3], v[2:3], 0, v[132:133]
	s_mov_b64 s[12:13], 0x10000
	global_load_dwordx4 v[216:219], v[2:3], off
	global_load_dwordx4 v[220:223], v[2:3], off offset:256
	v_lshl_add_u64 v[2:3], v[2:3], 0, s[12:13]
	global_load_dwordx4 v[224:227], v[2:3], off
	global_load_dwordx4 v[228:231], v[2:3], off offset:256
	v_lshl_add_u64 v[2:3], v[2:3], 0, s[12:13]
	global_load_dwordx4 v[232:235], v[2:3], off
	global_load_dwordx4 v[236:239], v[2:3], off offset:256
	v_lshl_add_u64 v[2:3], v[2:3], 0, s[12:13]
	global_load_dwordx4 v[240:243], v[2:3], off
	global_load_dwordx4 v[244:247], v[2:3], off offset:256
	s_mov_b64 s[12:13], 0x50000
	v_lshl_add_u64 v[2:3], v[2:3], 0, s[12:13]
	s_mov_b64 s[12:13], 0x10000
	global_load_dwordx4 v[198:201], v[2:3], off
	global_load_dwordx4 v[202:205], v[2:3], off offset:256
	v_lshl_add_u64 v[2:3], v[2:3], 0, s[12:13]
	global_load_dwordx4 v[206:209], v[2:3], off
	global_load_dwordx4 v[210:213], v[2:3], off offset:256
	v_lshl_add_u64 v[2:3], v[2:3], 0, s[12:13]
	global_load_dwordx4 v[164:167], v[2:3], off
	global_load_dwordx4 v[168:171], v[2:3], off offset:256
	v_lshl_add_u64 v[2:3], v[2:3], 0, s[12:13]
	global_load_dwordx4 v[172:175], v[2:3], off
	global_load_dwordx4 v[132:135], v[2:3], off offset:256
.Lp5_noearly:
	s_barrier
	s_add_i32 s68, s68, 2
	s_add_u32 s10, s10, 0x100
	s_addc_u32 s11, s11, 0
	s_cmp_gt_u32 s68, 13
	s_cbranch_scc1 .LBB0_549
.LBB0_547:
	s_cmpk_lg_i32 s10, 0x400
	s_cbranch_scc1 .LBB0_546
	s_and_b64 vcc, exec, s[8:9]
	s_cbranch_vccz .Lp5_hookwait
	v_add_u32_e32 v132, s29, v147
	v_lshl_add_u32 v2, v158, 3, s28
	v_ashrrev_i32_e32 v133, 31, v132
	v_ashrrev_i32_e32 v3, 31, v2
	v_lshlrev_b64 v[132:133], 12, v[132:133]
	v_lshlrev_b64 v[2:3], 1, v[2:3]
	v_lshl_add_u64 v[2:3], s[92:93], 0, v[2:3]
	v_lshl_add_u64 v[2:3], v[2:3], 0, v[132:133]
	s_mov_b64 s[12:13], 0x10000
	global_load_dwordx4 v[216:219], v[2:3], off
	global_load_dwordx4 v[220:223], v[2:3], off offset:256
	v_lshl_add_u64 v[2:3], v[2:3], 0, s[12:13]
	global_load_dwordx4 v[224:227], v[2:3], off
	global_load_dwordx4 v[228:231], v[2:3], off offset:256
	v_lshl_add_u64 v[2:3], v[2:3], 0, s[12:13]
	global_load_dwordx4 v[232:235], v[2:3], off
	global_load_dwordx4 v[236:239], v[2:3], off offset:256
	v_lshl_add_u64 v[2:3], v[2:3], 0, s[12:13]
	global_load_dwordx4 v[240:243], v[2:3], off
	global_load_dwordx4 v[244:247], v[2:3], off offset:256
	s_mov_b64 s[12:13], 0x50000
	v_lshl_add_u64 v[2:3], v[2:3], 0, s[12:13]
	s_mov_b64 s[12:13], 0x10000
	global_load_dwordx4 v[198:201], v[2:3], off
	global_load_dwordx4 v[202:205], v[2:3], off offset:256
	v_lshl_add_u64 v[2:3], v[2:3], 0, s[12:13]
	global_load_dwordx4 v[206:209], v[2:3], off
	global_load_dwordx4 v[210:213], v[2:3], off offset:256
	v_lshl_add_u64 v[2:3], v[2:3], 0, s[12:13]
	global_load_dwordx4 v[164:167], v[2:3], off
	global_load_dwordx4 v[168:171], v[2:3], off offset:256
	v_lshl_add_u64 v[2:3], v[2:3], 0, s[12:13]
	global_load_dwordx4 v[172:175], v[2:3], off
	global_load_dwordx4 v[132:135], v[2:3], off offset:256
.Lp5_hookwait:
	s_waitcnt vmcnt(15)
	v_lshlrev_b32_e32 v248, 16, v216
	v_and_b32_e32 v249, 0xffff0000, v216
	v_lshlrev_b32_e32 v250, 16, v217
	v_and_b32_e32 v251, 0xffff0000, v217
	v_lshlrev_b32_e32 v252, 16, v218
	v_and_b32_e32 v253, 0xffff0000, v218
	v_lshlrev_b32_e32 v176, 16, v219
	v_and_b32_e32 v177, 0xffff0000, v219
	v_pk_mul_f32 v[128:129], v[128:129], v[248:249]
	v_pk_mul_f32 v[130:131], v[130:131], v[250:251]
	v_pk_mul_f32 v[124:125], v[124:125], v[252:253]
	v_pk_mul_f32 v[126:127], v[126:127], v[176:177]
	s_waitcnt vmcnt(14)
	v_lshlrev_b32_e32 v248, 16, v220
	v_and_b32_e32 v249, 0xffff0000, v220
	v_lshlrev_b32_e32 v250, 16, v221
	v_and_b32_e32 v251, 0xffff0000, v221
	v_lshlrev_b32_e32 v252, 16, v222
	v_and_b32_e32 v253, 0xffff0000, v222
	v_lshlrev_b32_e32 v176, 16, v223
	v_and_b32_e32 v177, 0xffff0000, v223
	v_pk_mul_f32 v[120:121], v[120:121], v[248:249]
	v_pk_mul_f32 v[122:123], v[122:123], v[250:251]
	v_pk_mul_f32 v[116:117], v[116:117], v[252:253]
	v_pk_mul_f32 v[118:119], v[118:119], v[176:177]
	s_waitcnt vmcnt(13)
	v_lshlrev_b32_e32 v248, 16, v224
	v_and_b32_e32 v249, 0xffff0000, v224
	v_lshlrev_b32_e32 v250, 16, v225
	v_and_b32_e32 v251, 0xffff0000, v225
	v_lshlrev_b32_e32 v252, 16, v226
	v_and_b32_e32 v253, 0xffff0000, v226
	v_lshlrev_b32_e32 v176, 16, v227
	v_and_b32_e32 v177, 0xffff0000, v227
	v_pk_mul_f32 v[112:113], v[112:113], v[248:249]
	v_pk_mul_f32 v[114:115], v[114:115], v[250:251]
	v_pk_mul_f32 v[108:109], v[108:109], v[252:253]
	v_pk_mul_f32 v[110:111], v[110:111], v[176:177]
	s_waitcnt vmcnt(12)
	v_lshlrev_b32_e32 v248, 16, v228
	v_and_b32_e32 v249, 0xffff0000, v228
	v_lshlrev_b32_e32 v250, 16, v229
	v_and_b32_e32 v251, 0xffff0000, v229
	v_lshlrev_b32_e32 v252, 16, v230
	v_and_b32_e32 v253, 0xffff0000, v230
	v_lshlrev_b32_e32 v176, 16, v231
	v_and_b32_e32 v177, 0xffff0000, v231
	v_pk_mul_f32 v[104:105], v[104:105], v[248:249]
	v_pk_mul_f32 v[106:107], v[106:107], v[250:251]
	v_pk_mul_f32 v[100:101], v[100:101], v[252:253]
	v_pk_mul_f32 v[102:103], v[102:103], v[176:177]
	s_waitcnt vmcnt(11)
	v_lshlrev_b32_e32 v248, 16, v232
	v_and_b32_e32 v249, 0xffff0000, v232
	v_lshlrev_b32_e32 v250, 16, v233
	v_and_b32_e32 v251, 0xffff0000, v233
	v_lshlrev_b32_e32 v252, 16, v234
	v_and_b32_e32 v253, 0xffff0000, v234
	v_lshlrev_b32_e32 v176, 16, v235
	v_and_b32_e32 v177, 0xffff0000, v235
	v_pk_mul_f32 v[96:97], v[96:97], v[248:249]
	v_pk_mul_f32 v[98:99], v[98:99], v[250:251]
	v_pk_mul_f32 v[92:93], v[92:93], v[252:253]
	v_pk_mul_f32 v[94:95], v[94:95], v[176:177]
	s_waitcnt vmcnt(10)
	v_lshlrev_b32_e32 v248, 16, v236
	v_and_b32_e32 v249, 0xffff0000, v236
	v_lshlrev_b32_e32 v250, 16, v237
	v_and_b32_e32 v251, 0xffff0000, v237
	v_lshlrev_b32_e32 v252, 16, v238
	v_and_b32_e32 v253, 0xffff0000, v238
	v_lshlrev_b32_e32 v176, 16, v239
	v_and_b32_e32 v177, 0xffff0000, v239
	v_pk_mul_f32 v[88:89], v[88:89], v[248:249]
	v_pk_mul_f32 v[90:91], v[90:91], v[250:251]
	v_pk_mul_f32 v[84:85], v[84:85], v[252:253]
	v_pk_mul_f32 v[86:87], v[86:87], v[176:177]
	s_waitcnt vmcnt(9)
	v_lshlrev_b32_e32 v248, 16, v240
	v_and_b32_e32 v249, 0xffff0000, v240
	v_lshlrev_b32_e32 v250, 16, v241
	v_and_b32_e32 v251, 0xffff0000, v241
	v_lshlrev_b32_e32 v252, 16, v242
	v_and_b32_e32 v253, 0xffff0000, v242
	v_lshlrev_b32_e32 v176, 16, v243
	v_and_b32_e32 v177, 0xffff0000, v243
	v_pk_mul_f32 v[80:81], v[80:81], v[248:249]
	v_pk_mul_f32 v[82:83], v[82:83], v[250:251]
	v_pk_mul_f32 v[76:77], v[76:77], v[252:253]
	v_pk_mul_f32 v[78:79], v[78:79], v[176:177]
	s_waitcnt vmcnt(8)
	v_lshlrev_b32_e32 v248, 16, v244
	v_and_b32_e32 v249, 0xffff0000, v244
	v_lshlrev_b32_e32 v250, 16, v245
	v_and_b32_e32 v251, 0xffff0000, v245
	v_lshlrev_b32_e32 v252, 16, v246
	v_and_b32_e32 v253, 0xffff0000, v246
	v_lshlrev_b32_e32 v176, 16, v247
	v_and_b32_e32 v177, 0xffff0000, v247
	v_pk_mul_f32 v[72:73], v[72:73], v[248:249]
	v_pk_mul_f32 v[74:75], v[74:75], v[250:251]
	v_pk_mul_f32 v[68:69], v[68:69], v[252:253]
	v_pk_mul_f32 v[70:71], v[70:71], v[176:177]
	s_waitcnt vmcnt(7)
	v_lshlrev_b32_e32 v248, 16, v198
	v_and_b32_e32 v249, 0xffff0000, v198
	v_lshlrev_b32_e32 v250, 16, v199
	v_and_b32_e32 v251, 0xffff0000, v199
	v_lshlrev_b32_e32 v252, 16, v200
	v_and_b32_e32 v253, 0xffff0000, v200
	v_lshlrev_b32_e32 v176, 16, v201
	v_and_b32_e32 v177, 0xffff0000, v201
	v_pk_mul_f32 v[64:65], v[64:65], v[248:249]
	v_pk_mul_f32 v[66:67], v[66:67], v[250:251]
	v_pk_mul_f32 v[60:61], v[60:61], v[252:253]
	v_pk_mul_f32 v[62:63], v[62:63], v[176:177]
	s_waitcnt vmcnt(6)
	v_lshlrev_b32_e32 v248, 16, v202
	v_and_b32_e32 v249, 0xffff0000, v202
	v_lshlrev_b32_e32 v250, 16, v203
	v_and_b32_e32 v251, 0xffff0000, v203
	v_lshlrev_b32_e32 v252, 16, v204
	v_and_b32_e32 v253, 0xffff0000, v204
	v_lshlrev_b32_e32 v176, 16, v205
	v_and_b32_e32 v177, 0xffff0000, v205
	v_pk_mul_f32 v[56:57], v[56:57], v[248:249]
	v_pk_mul_f32 v[58:59], v[58:59], v[250:251]
	v_pk_mul_f32 v[52:53], v[52:53], v[252:253]
	v_pk_mul_f32 v[54:55], v[54:55], v[176:177]
	s_waitcnt vmcnt(5)
	v_lshlrev_b32_e32 v248, 16, v206
	v_and_b32_e32 v249, 0xffff0000, v206
	v_lshlrev_b32_e32 v250, 16, v207
	v_and_b32_e32 v251, 0xffff0000, v207
	v_lshlrev_b32_e32 v252, 16, v208
	v_and_b32_e32 v253, 0xffff0000, v208
	v_lshlrev_b32_e32 v176, 16, v209
	v_and_b32_e32 v177, 0xffff0000, v209
	v_pk_mul_f32 v[48:49], v[48:49], v[248:249]
	v_pk_mul_f32 v[50:51], v[50:51], v[250:251]
	v_pk_mul_f32 v[44:45], v[44:45], v[252:253]
	v_pk_mul_f32 v[46:47], v[46:47], v[176:177]
	s_waitcnt vmcnt(4)
	v_lshlrev_b32_e32 v248, 16, v210
	v_and_b32_e32 v249, 0xffff0000, v210
	v_lshlrev_b32_e32 v250, 16, v211
	v_and_b32_e32 v251, 0xffff0000, v211
	v_lshlrev_b32_e32 v252, 16, v212
	v_and_b32_e32 v253, 0xffff0000, v212
	v_lshlrev_b32_e32 v176, 16, v213
	v_and_b32_e32 v177, 0xffff0000, v213
	v_pk_mul_f32 v[40:41], v[40:41], v[248:249]
	v_pk_mul_f32 v[42:43], v[42:43], v[250:251]
	v_pk_mul_f32 v[36:37], v[36:37], v[252:253]
	v_pk_mul_f32 v[38:39], v[38:39], v[176:177]
	s_waitcnt vmcnt(3)
	v_lshlrev_b32_e32 v248, 16, v164
	v_and_b32_e32 v249, 0xffff0000, v164
	v_lshlrev_b32_e32 v250, 16, v165
	v_and_b32_e32 v251, 0xffff0000, v165
	v_lshlrev_b32_e32 v252, 16, v166
	v_and_b32_e32 v253, 0xffff0000, v166
	v_lshlrev_b32_e32 v176, 16, v167
	v_and_b32_e32 v177, 0xffff0000, v167
	v_pk_mul_f32 v[32:33], v[32:33], v[248:249]
	v_pk_mul_f32 v[34:35], v[34:35], v[250:251]
	v_pk_mul_f32 v[28:29], v[28:29], v[252:253]
	v_pk_mul_f32 v[30:31], v[30:31], v[176:177]
	s_waitcnt vmcnt(2)
	v_lshlrev_b32_e32 v248, 16, v168
	v_and_b32_e32 v249, 0xffff0000, v168
	v_lshlrev_b32_e32 v250, 16, v169
	v_and_b32_e32 v251, 0xffff0000, v169
	v_lshlrev_b32_e32 v252, 16, v170
	v_and_b32_e32 v253, 0xffff0000, v170
	v_lshlrev_b32_e32 v176, 16, v171
	v_and_b32_e32 v177, 0xffff0000, v171
	v_pk_mul_f32 v[24:25], v[24:25], v[248:249]
	v_pk_mul_f32 v[26:27], v[26:27], v[250:251]
	v_pk_mul_f32 v[20:21], v[20:21], v[252:253]
	v_pk_mul_f32 v[22:23], v[22:23], v[176:177]
	s_waitcnt vmcnt(1)
	v_lshlrev_b32_e32 v248, 16, v172
	v_and_b32_e32 v249, 0xffff0000, v172
	v_lshlrev_b32_e32 v250, 16, v173
	v_and_b32_e32 v251, 0xffff0000, v173
	v_lshlrev_b32_e32 v252, 16, v174
	v_and_b32_e32 v253, 0xffff0000, v174
	v_lshlrev_b32_e32 v176, 16, v175
	v_and_b32_e32 v177, 0xffff0000, v175
	v_pk_mul_f32 v[16:17], v[16:17], v[248:249]
	v_pk_mul_f32 v[18:19], v[18:19], v[250:251]
	v_pk_mul_f32 v[12:13], v[12:13], v[252:253]
	v_pk_mul_f32 v[14:15], v[14:15], v[176:177]
	s_waitcnt vmcnt(0)
	v_lshlrev_b32_e32 v248, 16, v132
	v_and_b32_e32 v249, 0xffff0000, v132
	v_lshlrev_b32_e32 v250, 16, v133
	v_and_b32_e32 v251, 0xffff0000, v133
	v_lshlrev_b32_e32 v252, 16, v134
	v_and_b32_e32 v253, 0xffff0000, v134
	v_lshlrev_b32_e32 v176, 16, v135
	v_and_b32_e32 v177, 0xffff0000, v135
	v_pk_mul_f32 v[8:9], v[8:9], v[248:249]
	v_pk_mul_f32 v[10:11], v[10:11], v[250:251]
	v_pk_mul_f32 v[4:5], v[4:5], v[252:253]
	v_pk_mul_f32 v[6:7], v[6:7], v[176:177]
	s_branch .LBB0_546
